# scan: next-chunk q/k/v/gate load addresses stepped by a signed row stride (16 consecutive rows) instead of recomputed per row
# baseline (speedup 1.0000x reference)
.LBB0_217:
	s_or_b64 exec, exec, s[18:19]
	v_cndmask_b32_e64 v37, 0, v37, s[44:45]
	v_add_f32_e32 v21, v21, v37
	v_cndmask_b32_e64 v21, v37, v21, s[46:47]
	v_add_f32_e32 v18, v18, v21
	v_cndmask_b32_e64 v18, v21, v18, s[48:49]
	v_add_f32_e32 v19, v19, v18
	v_cndmask_b32_e64 v18, v18, v19, s[50:51]
	v_add_f32_e32 v19, v36, v18
	v_mul_f32_e32 v21, 0x3fb8aa3b, v19
	v_exp_f32_e32 v21, v21
	v_lshlrev_b32_e32 v38, 16, v75
	s_nop 0
	v_mul_f32_e32 v230, 0xbfb8aa3b, v19
	v_mul_f32_e32 v21, v21, v38
	v_lshlrev_b32_e32 v39, 16, v77
	v_exp_f32_e32 v230, v230
	v_cvt_pk_bf16_f32 v21, v21, s0
	v_sub_f32_e32 v19, v20, v19
	ds_write_b16 v124, v21
	s_nop 0
	v_mul_f32_e32 v19, 0x3fb8aa3b, v19
	v_mul_f32_e32 v21, v230, v39
	v_exp_f32_e32 v19, v19
	v_cvt_pk_bf16_f32 v21, v21, s0
	ds_write_b16 v124, v21 offset:9216
	s_nop 0
	v_add_f32_e32 v21, v35, v18
	v_mul_f32_e32 v35, 0x3fb8aa3b, v21
	v_mul_f32_e32 v19, v19, v39
	v_exp_f32_e32 v35, v35
	v_cvt_pk_bf16_f32 v19, v19, s0
	v_lshlrev_b32_e32 v40, 16, v150
	ds_write_b16 v125, v19 offset:18432
	s_nop 0
	v_mul_f32_e32 v19, 0xbfb8aa3b, v21
	v_mul_f32_e32 v35, v35, v40
	v_exp_f32_e32 v19, v19
	v_cvt_pk_bf16_f32 v35, v35, s0
	v_lshlrev_b32_e32 v41, 16, v151
	ds_write_b16 v126, v35
	s_nop 0
	v_sub_f32_e32 v21, v20, v21
	v_mul_f32_e32 v21, 0x3fb8aa3b, v21
	v_mul_f32_e32 v19, v19, v41
	v_exp_f32_e32 v21, v21
	v_cvt_pk_bf16_f32 v19, v19, s0
	ds_write_b16 v126, v19 offset:9216
	s_nop 0
	v_add_f32_e32 v19, v34, v18
	v_mul_f32_e32 v34, 0x3fb8aa3b, v19
	v_mul_f32_e32 v21, v21, v41
	v_exp_f32_e32 v34, v34
	v_cvt_pk_bf16_f32 v21, v21, s0
	v_lshlrev_b32_e32 v42, 16, v154
	ds_write_b16 v125, v21 offset:18434
	s_nop 0
	v_mul_f32_e32 v21, 0xbfb8aa3b, v19
	v_mul_f32_e32 v34, v34, v42
	v_exp_f32_e32 v21, v21
	v_cvt_pk_bf16_f32 v34, v34, s0
	v_lshlrev_b32_e32 v43, 16, v155
	ds_write_b16 v127, v34
	s_nop 0
	v_sub_f32_e32 v19, v20, v19
	v_mul_f32_e32 v19, 0x3fb8aa3b, v19
	v_mul_f32_e32 v21, v21, v43
	v_exp_f32_e32 v19, v19
	v_cvt_pk_bf16_f32 v21, v21, s0
	ds_write_b16 v127, v21 offset:9216
	s_nop 0
	v_add_f32_e32 v21, v33, v18
	v_mul_f32_e32 v33, 0x3fb8aa3b, v21
	v_mul_f32_e32 v19, v19, v43
	v_exp_f32_e32 v33, v33
	v_cvt_pk_bf16_f32 v19, v19, s0
	v_lshlrev_b32_e32 v44, 16, v158
	ds_write_b16 v125, v19 offset:18436
	s_nop 0
	v_mul_f32_e32 v19, 0xbfb8aa3b, v21
	v_mul_f32_e32 v33, v33, v44
	v_exp_f32_e32 v19, v19
	v_cvt_pk_bf16_f32 v33, v33, s0
	v_lshlrev_b32_e32 v45, 16, v159
	ds_write_b16 v128, v33
	s_nop 0
	v_sub_f32_e32 v21, v20, v21
	v_mul_f32_e32 v21, 0x3fb8aa3b, v21
	v_mul_f32_e32 v19, v19, v45
	v_exp_f32_e32 v21, v21
	v_cvt_pk_bf16_f32 v19, v19, s0
	ds_write_b16 v128, v19 offset:9216
	s_nop 0
	v_add_f32_e32 v19, v32, v18
	v_mul_f32_e32 v32, 0x3fb8aa3b, v19
	v_mul_f32_e32 v21, v21, v45
	v_exp_f32_e32 v32, v32
	v_cvt_pk_bf16_f32 v21, v21, s0
	v_lshlrev_b32_e32 v46, 16, v162
	ds_write_b16 v125, v21 offset:18438
	s_nop 0
	v_mul_f32_e32 v21, 0xbfb8aa3b, v19
	v_mul_f32_e32 v32, v32, v46
	v_exp_f32_e32 v21, v21
	v_cvt_pk_bf16_f32 v32, v32, s0
	v_lshlrev_b32_e32 v47, 16, v163
	ds_write_b16 v129, v32
	s_nop 0
	v_sub_f32_e32 v19, v20, v19
	v_mul_f32_e32 v19, 0x3fb8aa3b, v19
	v_mul_f32_e32 v21, v21, v47
	v_exp_f32_e32 v19, v19
	v_cvt_pk_bf16_f32 v21, v21, s0
	ds_write_b16 v129, v21 offset:9216
	s_nop 0
	v_add_f32_e32 v21, v31, v18
	v_mul_f32_e32 v31, 0x3fb8aa3b, v21
	v_mul_f32_e32 v19, v19, v47
	v_exp_f32_e32 v31, v31
	v_cvt_pk_bf16_f32 v19, v19, s0
	v_lshlrev_b32_e32 v48, 16, v166
	ds_write_b16 v125, v19 offset:18440
	s_nop 0
	v_mul_f32_e32 v19, 0xbfb8aa3b, v21
	v_mul_f32_e32 v31, v31, v48
	v_exp_f32_e32 v19, v19
	v_cvt_pk_bf16_f32 v31, v31, s0
	v_lshlrev_b32_e32 v49, 16, v167
	ds_write_b16 v130, v31
	s_nop 0
	v_sub_f32_e32 v21, v20, v21
	v_mul_f32_e32 v21, 0x3fb8aa3b, v21
	v_mul_f32_e32 v19, v19, v49
	v_exp_f32_e32 v21, v21
	v_cvt_pk_bf16_f32 v19, v19, s0
	ds_write_b16 v130, v19 offset:9216
	s_nop 0
	v_add_f32_e32 v19, v30, v18
	v_mul_f32_e32 v30, 0x3fb8aa3b, v19
	v_mul_f32_e32 v21, v21, v49
	v_exp_f32_e32 v30, v30
	v_cvt_pk_bf16_f32 v21, v21, s0
	v_lshlrev_b32_e32 v50, 16, v171
	ds_write_b16 v125, v21 offset:18442
	s_nop 0
	v_mul_f32_e32 v21, 0xbfb8aa3b, v19
	v_mul_f32_e32 v30, v30, v50
	v_exp_f32_e32 v21, v21
	v_cvt_pk_bf16_f32 v30, v30, s0
	v_lshlrev_b32_e32 v51, 16, v172
	ds_write_b16 v131, v30
	s_nop 0
	v_sub_f32_e32 v19, v20, v19
	v_mul_f32_e32 v19, 0x3fb8aa3b, v19
	v_mul_f32_e32 v21, v21, v51
	v_exp_f32_e32 v19, v19
	v_cvt_pk_bf16_f32 v21, v21, s0
	ds_write_b16 v131, v21 offset:9216
	s_nop 0
	v_add_f32_e32 v21, v29, v18
	v_mul_f32_e32 v29, 0x3fb8aa3b, v21
	v_mul_f32_e32 v19, v19, v51
	v_exp_f32_e32 v29, v29
	v_cvt_pk_bf16_f32 v19, v19, s0
	v_lshlrev_b32_e32 v52, 16, v175
	ds_write_b16 v125, v19 offset:18444
	s_nop 0
	v_mul_f32_e32 v19, 0xbfb8aa3b, v21
	v_mul_f32_e32 v29, v29, v52
	v_exp_f32_e32 v19, v19
	v_cvt_pk_bf16_f32 v29, v29, s0
	v_lshlrev_b32_e32 v53, 16, v176
	ds_write_b16 v132, v29
	s_nop 0
	v_sub_f32_e32 v21, v20, v21
	v_mul_f32_e32 v21, 0x3fb8aa3b, v21
	v_mul_f32_e32 v19, v19, v53
	v_exp_f32_e32 v21, v21
	v_cvt_pk_bf16_f32 v19, v19, s0
	ds_write_b16 v132, v19 offset:9216
	s_nop 0
	v_add_f32_e32 v19, v28, v18
	v_mul_f32_e32 v28, 0x3fb8aa3b, v19
	v_mul_f32_e32 v21, v21, v53
	v_exp_f32_e32 v28, v28
	v_cvt_pk_bf16_f32 v21, v21, s0
	v_lshlrev_b32_e32 v54, 16, v179
	ds_write_b16 v125, v21 offset:18446
	s_nop 0
	v_mul_f32_e32 v21, 0xbfb8aa3b, v19
	v_mul_f32_e32 v28, v28, v54
	v_exp_f32_e32 v21, v21
	v_cvt_pk_bf16_f32 v28, v28, s0
	v_lshlrev_b32_e32 v55, 16, v180
	ds_write_b16 v133, v28
	s_nop 0
	v_sub_f32_e32 v19, v20, v19
	v_mul_f32_e32 v19, 0x3fb8aa3b, v19
	v_mul_f32_e32 v21, v21, v55
	v_exp_f32_e32 v19, v19
	v_cvt_pk_bf16_f32 v21, v21, s0
	ds_write_b16 v133, v21 offset:9216
	s_nop 0
	v_add_f32_e32 v21, v27, v18
	v_mul_f32_e32 v27, 0x3fb8aa3b, v21
	v_mul_f32_e32 v19, v19, v55
	v_exp_f32_e32 v27, v27
	v_cvt_pk_bf16_f32 v19, v19, s0
	v_lshlrev_b32_e32 v56, 16, v183
	ds_write_b16 v125, v19 offset:18448
	s_nop 0
	v_mul_f32_e32 v19, 0xbfb8aa3b, v21
	v_mul_f32_e32 v27, v27, v56
	v_exp_f32_e32 v19, v19
	v_cvt_pk_bf16_f32 v27, v27, s0
	v_lshlrev_b32_e32 v57, 16, v184
	ds_write_b16 v134, v27
	s_nop 0
	v_sub_f32_e32 v21, v20, v21
	v_mul_f32_e32 v21, 0x3fb8aa3b, v21
	v_mul_f32_e32 v19, v19, v57
	v_exp_f32_e32 v21, v21
	v_cvt_pk_bf16_f32 v19, v19, s0
	ds_write_b16 v134, v19 offset:9216
	s_nop 0
	v_add_f32_e32 v19, v26, v18
	v_mul_f32_e32 v26, 0x3fb8aa3b, v19
	v_mul_f32_e32 v21, v21, v57
	v_exp_f32_e32 v26, v26
	v_cvt_pk_bf16_f32 v21, v21, s0
	v_lshlrev_b32_e32 v58, 16, v187
	ds_write_b16 v125, v21 offset:18450
	s_nop 0
	v_mul_f32_e32 v21, 0xbfb8aa3b, v19
	v_mul_f32_e32 v26, v26, v58
	v_exp_f32_e32 v21, v21
	v_cvt_pk_bf16_f32 v26, v26, s0
	v_lshlrev_b32_e32 v59, 16, v188
	ds_write_b16 v135, v26
	s_nop 0
	v_sub_f32_e32 v19, v20, v19
	v_mul_f32_e32 v19, 0x3fb8aa3b, v19
	v_mul_f32_e32 v21, v21, v59
	v_exp_f32_e32 v19, v19
	v_cvt_pk_bf16_f32 v21, v21, s0
	ds_write_b16 v135, v21 offset:9216
	s_nop 0
	v_add_f32_e32 v21, v25, v18
	v_mul_f32_e32 v25, 0x3fb8aa3b, v21
	v_mul_f32_e32 v19, v19, v59
	v_exp_f32_e32 v25, v25
	v_cvt_pk_bf16_f32 v19, v19, s0
	v_lshlrev_b32_e32 v60, 16, v191
	ds_write_b16 v125, v19 offset:18452
	s_nop 0
	v_mul_f32_e32 v19, 0xbfb8aa3b, v21
	v_mul_f32_e32 v25, v25, v60
	v_exp_f32_e32 v19, v19
	v_cvt_pk_bf16_f32 v25, v25, s0
	v_lshlrev_b32_e32 v61, 16, v192
	ds_write_b16 v136, v25
	s_nop 0
	v_sub_f32_e32 v21, v20, v21
	v_mul_f32_e32 v21, 0x3fb8aa3b, v21
	v_mul_f32_e32 v19, v19, v61
	v_exp_f32_e32 v21, v21
	v_cvt_pk_bf16_f32 v19, v19, s0
	ds_write_b16 v136, v19 offset:9216
	s_nop 0
	v_add_f32_e32 v19, v24, v18
	v_mul_f32_e32 v24, 0x3fb8aa3b, v19
	v_mul_f32_e32 v21, v21, v61
	v_exp_f32_e32 v24, v24
	v_cvt_pk_bf16_f32 v21, v21, s0
	v_lshlrev_b32_e32 v62, 16, v212
	ds_write_b16 v125, v21 offset:18454
	s_nop 0
	v_mul_f32_e32 v21, 0xbfb8aa3b, v19
	v_mul_f32_e32 v24, v24, v62
	v_exp_f32_e32 v21, v21
	v_cvt_pk_bf16_f32 v24, v24, s0
	v_lshlrev_b32_e32 v63, 16, v213
	ds_write_b16 v137, v24
	s_nop 0
	v_sub_f32_e32 v19, v20, v19
	v_mul_f32_e32 v19, 0x3fb8aa3b, v19
	v_mul_f32_e32 v21, v21, v63
	v_exp_f32_e32 v19, v19
	v_cvt_pk_bf16_f32 v21, v21, s0
	ds_write_b16 v137, v21 offset:9216
	s_nop 0
	v_add_f32_e32 v21, v23, v18
	v_mul_f32_e32 v23, 0x3fb8aa3b, v21
	v_mul_f32_e32 v19, v19, v63
	v_exp_f32_e32 v23, v23
	v_cvt_pk_bf16_f32 v19, v19, s0
	v_lshlrev_b32_e32 v64, 16, v216
	ds_write_b16 v125, v19 offset:18456
	s_nop 0
	v_mul_f32_e32 v19, 0xbfb8aa3b, v21
	v_mul_f32_e32 v23, v23, v64
	v_exp_f32_e32 v19, v19
	v_cvt_pk_bf16_f32 v23, v23, s0
	v_lshlrev_b32_e32 v65, 16, v217
	ds_write_b16 v138, v23
	s_nop 0
	v_sub_f32_e32 v21, v20, v21
	v_mul_f32_e32 v21, 0x3fb8aa3b, v21
	v_mul_f32_e32 v19, v19, v65
	v_exp_f32_e32 v21, v21
	v_cvt_pk_bf16_f32 v19, v19, s0
	ds_write_b16 v138, v19 offset:9216
	s_nop 0
	v_add_f32_e32 v19, v22, v18
	v_mul_f32_e32 v22, 0x3fb8aa3b, v19
	v_mul_f32_e32 v21, v21, v65
	v_exp_f32_e32 v22, v22
	v_cvt_pk_bf16_f32 v21, v21, s0
	v_lshlrev_b32_e32 v228, 16, v220
	ds_write_b16 v125, v21 offset:18458
	s_nop 0
	v_mul_f32_e32 v21, 0xbfb8aa3b, v19
	v_mul_f32_e32 v22, v22, v228
	v_exp_f32_e32 v21, v21
	v_cvt_pk_bf16_f32 v22, v22, s0
	v_lshlrev_b32_e32 v36, 16, v221
	ds_write_b16 v139, v22
	s_nop 0
	v_sub_f32_e32 v19, v20, v19
	v_mul_f32_e32 v19, 0x3fb8aa3b, v19
	v_mul_f32_e32 v21, v21, v36
	v_exp_f32_e32 v19, v19
	v_cvt_pk_bf16_f32 v21, v21, s0
	ds_write_b16 v139, v21 offset:9216
	s_nop 0
	v_add_f32_e32 v0, v0, v18
	v_mul_f32_e32 v18, 0x3fb8aa3b, v0
	v_mul_f32_e32 v19, v19, v36
	v_exp_f32_e32 v18, v18
	v_cvt_pk_bf16_f32 v19, v19, s0
	v_lshlrev_b32_e32 v37, 16, v224
	ds_write_b16 v125, v19 offset:18460
	s_nop 0
	v_mul_f32_e32 v19, 0xbfb8aa3b, v0
	v_mul_f32_e32 v18, v18, v37
	v_lshlrev_b32_e32 v229, 16, v225
	v_exp_f32_e32 v19, v19
	v_cvt_pk_bf16_f32 v18, v18, s0
	v_sub_f32_e32 v0, v20, v0
	ds_write_b16 v140, v18
	s_nop 0
	v_mul_f32_e32 v0, 0x3fb8aa3b, v0
	v_mul_f32_e32 v18, v19, v229
	v_exp_f32_e32 v0, v0
	v_cvt_pk_bf16_f32 v18, v18, s0
	ds_write_b16 v140, v18 offset:9216
	s_nop 0
	s_add_i32 s13, s12, 1
	v_mul_f32_e32 v0, v0, v229
	v_cvt_pk_bf16_f32 v0, v0, s0
	s_cmp_ge_u32 s13, s35
	ds_write_b16 v125, v0 offset:18462
	s_waitcnt lgkmcnt(0)
	s_barrier
	s_cbranch_scc1 .LBB0_250
	s_lshl_b32 s18, s13, 6
	v_add_u32_e32 v0, s18, v67
	v_xad_u32 v18, v0, -1, s26
	v_cndmask_b32_e64 v0, v18, v0, s[84:85]
	v_add_u32_e32 v20, s33, v0
	v_ashrrev_i32_e32 v21, 31, v20
	v_lshlrev_b64 v[18:19], 9, v[20:21]
	v_lshlrev_b64 v[20:21], 10, v[20:21]
	v_mov_b32_e32 v244, 0x200
	v_mov_b32_e32 v22, 0xfffffe00
	v_mov_b32_e32 v245, 0
	v_mov_b32_e32 v23, -1
	v_lshl_add_u64 v[236:237], v[80:81], 0, v[18:19]
	v_lshl_add_u64 v[238:239], v[82:83], 0, v[18:19]
	v_lshl_add_u64 v[240:241], v[84:85], 0, v[20:21]
	v_lshl_add_u64 v[242:243], v[18:19], 2, v[78:79]
	v_cndmask_b32_e64 v244, v22, v244, s[84:85]
	v_cndmask_b32_e64 v245, v23, v245, s[84:85]
	global_load_ushort v75, v[236:237], off
	global_load_ushort v148, v[240:241], off
	global_load_ushort v77, v[238:239], off
	s_and_b64 vcc, exec, s[86:87]
	v_mov_b32_e32 v149, v147
	s_cbranch_vccnz .Lhw_scan_g0
	global_load_dword v149, v[242:243], off
.Lhw_scan_g0:
	v_lshl_add_u64 v[236:237], v[244:245], 0, v[236:237]
	v_lshl_add_u64 v[238:239], v[244:245], 0, v[238:239]
	v_lshl_add_u64 v[240:241], v[244:245], 1, v[240:241]
	v_lshl_add_u64 v[242:243], v[244:245], 2, v[242:243]
	global_load_ushort v150, v[236:237], off
	global_load_ushort v152, v[240:241], off
	global_load_ushort v151, v[238:239], off
	s_and_b64 vcc, exec, s[86:87]
	v_mov_b32_e32 v153, v147
	s_cbranch_vccnz .Lhw_scan_g1
	global_load_dword v153, v[242:243], off
.Lhw_scan_g1:
	v_lshl_add_u64 v[236:237], v[244:245], 0, v[236:237]
	v_lshl_add_u64 v[238:239], v[244:245], 0, v[238:239]
	v_lshl_add_u64 v[240:241], v[244:245], 1, v[240:241]
	v_lshl_add_u64 v[242:243], v[244:245], 2, v[242:243]
	global_load_ushort v154, v[236:237], off
	global_load_ushort v156, v[240:241], off
	global_load_ushort v155, v[238:239], off
	s_and_b64 vcc, exec, s[86:87]
	v_mov_b32_e32 v157, v147
	s_cbranch_vccnz .Lhw_scan_g2
	global_load_dword v157, v[242:243], off
.Lhw_scan_g2:
	v_lshl_add_u64 v[236:237], v[244:245], 0, v[236:237]
	v_lshl_add_u64 v[238:239], v[244:245], 0, v[238:239]
	v_lshl_add_u64 v[240:241], v[244:245], 1, v[240:241]
	v_lshl_add_u64 v[242:243], v[244:245], 2, v[242:243]
	global_load_ushort v158, v[236:237], off
	global_load_ushort v160, v[240:241], off
	global_load_ushort v159, v[238:239], off
	s_and_b64 vcc, exec, s[86:87]
	v_mov_b32_e32 v161, v147
	s_cbranch_vccnz .Lhw_scan_g3
	global_load_dword v161, v[242:243], off
.Lhw_scan_g3:
	v_lshl_add_u64 v[236:237], v[244:245], 0, v[236:237]
	v_lshl_add_u64 v[238:239], v[244:245], 0, v[238:239]
	v_lshl_add_u64 v[240:241], v[244:245], 1, v[240:241]
	v_lshl_add_u64 v[242:243], v[244:245], 2, v[242:243]
	global_load_ushort v162, v[236:237], off
	global_load_ushort v164, v[240:241], off
	global_load_ushort v163, v[238:239], off
	s_and_b64 vcc, exec, s[86:87]
	v_mov_b32_e32 v165, v147
	s_cbranch_vccnz .Lhw_scan_g4
	global_load_dword v165, v[242:243], off
.Lhw_scan_g4:
	v_lshl_add_u64 v[236:237], v[244:245], 0, v[236:237]
	v_lshl_add_u64 v[238:239], v[244:245], 0, v[238:239]
	v_lshl_add_u64 v[240:241], v[244:245], 1, v[240:241]
	v_lshl_add_u64 v[242:243], v[244:245], 2, v[242:243]
	global_load_ushort v166, v[236:237], off
	global_load_ushort v168, v[240:241], off
	global_load_ushort v167, v[238:239], off
	s_and_b64 vcc, exec, s[86:87]
	v_mov_b32_e32 v169, v147
	s_cbranch_vccnz .Lhw_scan_g5
	global_load_dword v169, v[242:243], off
.Lhw_scan_g5:
	v_lshl_add_u64 v[236:237], v[244:245], 0, v[236:237]
	v_lshl_add_u64 v[238:239], v[244:245], 0, v[238:239]
	v_lshl_add_u64 v[240:241], v[244:245], 1, v[240:241]
	v_lshl_add_u64 v[242:243], v[244:245], 2, v[242:243]
	global_load_ushort v171, v[236:237], off
	global_load_ushort v173, v[240:241], off
	global_load_ushort v172, v[238:239], off
	s_and_b64 vcc, exec, s[86:87]
	v_mov_b32_e32 v174, v147
	s_cbranch_vccnz .Lhw_scan_g6
	global_load_dword v174, v[242:243], off
.Lhw_scan_g6:
	v_lshl_add_u64 v[236:237], v[244:245], 0, v[236:237]
	v_lshl_add_u64 v[238:239], v[244:245], 0, v[238:239]
	v_lshl_add_u64 v[240:241], v[244:245], 1, v[240:241]
	v_lshl_add_u64 v[242:243], v[244:245], 2, v[242:243]
	global_load_ushort v175, v[236:237], off
	global_load_ushort v177, v[240:241], off
	global_load_ushort v176, v[238:239], off
	s_and_b64 vcc, exec, s[86:87]
	v_mov_b32_e32 v178, v147
	s_cbranch_vccnz .Lhw_scan_g7
	global_load_dword v178, v[242:243], off
.Lhw_scan_g7:
	v_lshl_add_u64 v[236:237], v[244:245], 0, v[236:237]
	v_lshl_add_u64 v[238:239], v[244:245], 0, v[238:239]
	v_lshl_add_u64 v[240:241], v[244:245], 1, v[240:241]
	v_lshl_add_u64 v[242:243], v[244:245], 2, v[242:243]
	global_load_ushort v179, v[236:237], off
	global_load_ushort v181, v[240:241], off
	global_load_ushort v180, v[238:239], off
	s_and_b64 vcc, exec, s[86:87]
	v_mov_b32_e32 v182, v147
	s_cbranch_vccnz .Lhw_scan_g8
	global_load_dword v182, v[242:243], off
.Lhw_scan_g8:
	v_lshl_add_u64 v[236:237], v[244:245], 0, v[236:237]
	v_lshl_add_u64 v[238:239], v[244:245], 0, v[238:239]
	v_lshl_add_u64 v[240:241], v[244:245], 1, v[240:241]
	v_lshl_add_u64 v[242:243], v[244:245], 2, v[242:243]
	global_load_ushort v183, v[236:237], off
	global_load_ushort v185, v[240:241], off
	global_load_ushort v184, v[238:239], off
	s_and_b64 vcc, exec, s[86:87]
	v_mov_b32_e32 v186, v147
	s_cbranch_vccnz .Lhw_scan_g9
	global_load_dword v186, v[242:243], off
.Lhw_scan_g9:
	v_lshl_add_u64 v[236:237], v[244:245], 0, v[236:237]
	v_lshl_add_u64 v[238:239], v[244:245], 0, v[238:239]
	v_lshl_add_u64 v[240:241], v[244:245], 1, v[240:241]
	v_lshl_add_u64 v[242:243], v[244:245], 2, v[242:243]
	global_load_ushort v187, v[236:237], off
	global_load_ushort v189, v[240:241], off
	global_load_ushort v188, v[238:239], off
	s_and_b64 vcc, exec, s[86:87]
	v_mov_b32_e32 v190, v147
	s_cbranch_vccnz .Lhw_scan_g10
	global_load_dword v190, v[242:243], off
.Lhw_scan_g10:
	v_lshl_add_u64 v[236:237], v[244:245], 0, v[236:237]
	v_lshl_add_u64 v[238:239], v[244:245], 0, v[238:239]
	v_lshl_add_u64 v[240:241], v[244:245], 1, v[240:241]
	v_lshl_add_u64 v[242:243], v[244:245], 2, v[242:243]
	global_load_ushort v191, v[236:237], off
	global_load_ushort v193, v[240:241], off
	global_load_ushort v192, v[238:239], off
	s_and_b64 vcc, exec, s[86:87]
	v_mov_b32_e32 v211, v147
	s_cbranch_vccnz .Lhw_scan_g11
	global_load_dword v211, v[242:243], off
.Lhw_scan_g11:
	v_lshl_add_u64 v[236:237], v[244:245], 0, v[236:237]
	v_lshl_add_u64 v[238:239], v[244:245], 0, v[238:239]
	v_lshl_add_u64 v[240:241], v[244:245], 1, v[240:241]
	v_lshl_add_u64 v[242:243], v[244:245], 2, v[242:243]
	global_load_ushort v212, v[236:237], off
	global_load_ushort v214, v[240:241], off
	global_load_ushort v213, v[238:239], off
	s_and_b64 vcc, exec, s[86:87]
	v_mov_b32_e32 v215, v147
	s_cbranch_vccnz .Lhw_scan_g12
	global_load_dword v215, v[242:243], off
.Lhw_scan_g12:
	v_lshl_add_u64 v[236:237], v[244:245], 0, v[236:237]
	v_lshl_add_u64 v[238:239], v[244:245], 0, v[238:239]
	v_lshl_add_u64 v[240:241], v[244:245], 1, v[240:241]
	v_lshl_add_u64 v[242:243], v[244:245], 2, v[242:243]
	global_load_ushort v216, v[236:237], off
	global_load_ushort v218, v[240:241], off
	global_load_ushort v217, v[238:239], off
	s_and_b64 vcc, exec, s[86:87]
	v_mov_b32_e32 v219, v147
	s_cbranch_vccnz .Lhw_scan_g13
	global_load_dword v219, v[242:243], off
.Lhw_scan_g13:
	v_lshl_add_u64 v[236:237], v[244:245], 0, v[236:237]
	v_lshl_add_u64 v[238:239], v[244:245], 0, v[238:239]
	v_lshl_add_u64 v[240:241], v[244:245], 1, v[240:241]
	v_lshl_add_u64 v[242:243], v[244:245], 2, v[242:243]
	global_load_ushort v220, v[236:237], off
	global_load_ushort v222, v[240:241], off
	global_load_ushort v221, v[238:239], off
	s_and_b64 vcc, exec, s[86:87]
	v_mov_b32_e32 v223, v147
	s_cbranch_vccnz .Lhw_scan_g14
	global_load_dword v223, v[242:243], off
.Lhw_scan_g14:
	v_lshl_add_u64 v[236:237], v[244:245], 0, v[236:237]
	v_lshl_add_u64 v[238:239], v[244:245], 0, v[238:239]
	v_lshl_add_u64 v[240:241], v[244:245], 1, v[240:241]
	v_lshl_add_u64 v[242:243], v[244:245], 2, v[242:243]
	global_load_ushort v224, v[236:237], off
	global_load_ushort v226, v[240:241], off
	global_load_ushort v225, v[238:239], off
	s_and_b64 vcc, exec, s[86:87]
	v_mov_b32_e32 v227, v147
	s_cbranch_vccnz .Lhw_scan_g15
	global_load_dword v227, v[242:243], off
.Lhw_scan_g15:
.LBB0_250:
	v_add_u32_e32 v38, v123, v122
	v_add_u32_e32 v0, v121, v122
	ds_read_b128 v[18:21], v38 offset:36864
	ds_read_b128 v[50:53], v0
	ds_read_b128 v[34:37], v38 offset:36896
	ds_read_b128 v[54:57], v0 offset:32
	ds_read_b128 v[40:43], v38 offset:36928
	ds_read_b128 v[58:61], v0 offset:64
	ds_read_b128 v[44:47], v38 offset:36960
	ds_read_b128 v[62:65], v0 offset:96
	s_mov_b64 s[18:19], 0
	v_mov_b32_e32 v228, v143
	v_mov_b32_e32 v229, v142
	v_mov_b32_e32 v230, v141
	ds_read_b128 v[232:235], v143
	ds_read_b128 v[236:239], v143 offset:32
	ds_read_b128 v[240:243], v143 offset:64
	ds_read_b128 v[250:253], v143 offset:96
	s_waitcnt lgkmcnt(10)
	v_mfma_f32_32x32x16_bf16 v[18:33], v[18:21], v[50:53], 0
	s_waitcnt lgkmcnt(8)
	v_mfma_f32_32x32x16_bf16 v[18:33], v[34:37], v[54:57], v[18:33]
	s_waitcnt lgkmcnt(6)
	v_mfma_f32_32x32x16_bf16 v[18:33], v[40:43], v[58:61], v[18:33]
	s_waitcnt lgkmcnt(4)
	v_mfma_f32_32x32x16_bf16 v[18:33], v[44:47], v[62:65], v[18:33]
	s_branch .LBB0_252
